# ssd_pre: the three prior-row conv tap loads issued together with one wait (was load/wait x3)
# baseline (speedup 1.0000x reference)
; __device__ __forceinline__ bfr f2bf(float f) { return (bfr)(pack2(f, f) & 0xffffu); }
; __device__ __forceinline__ float bf2f(bfr b) { return __uint_as_float(((unsigned)b) << 16); }
; __device__ void ssd_pre(const KP& p, int l, int cid, int g) {
;     ...
;     float w0[5], w1[5];
; #pragma unroll
;     for (int k = 0; k < 4; ++k) { w0[k] = convw[k * 1024 + ch]; w1[k] = convw[k * 1024 + ch + 1]; }
;     w0[4] = convb[ch]; w1[4] = convb[ch + 1];
;     float a0[3], a1[3];
; #pragma unroll
;     for (int k = 0; k < 3; ++k) {
;       int rr = rs_ - 3 + k;
;       float x0 = 0.f, x1 = 0.f;
;       if (rr >= 0) { unsigned u = *(const unsigned*)(proj + (size_t)(r0 + rr) * NIN + 512 + ch); x0 = __uint_as_float(u << 16); x1 = __uint_as_float(u & 0xffff0000u); }
;       else if (!first) { unsigned u = *(const unsigned*)(tails + ((size_t)(cid - 1) * 3 + (rr + 3)) * 1024 + ch); x0 = __uint_as_float(u << 16); x1 = __uint_as_float(u & 0xffff0000u); }
;       else if (!prompt) { const float* sp = p.in[2] + (((size_t)l * 8 + sb) * 3 + (rr + 3)) * 1024 + ch; x0 = bf2f(f2bf(sp[0])); x1 = bf2f(f2bf(sp[1])); }
;       a0[k] = x0; a1[k] = x1;
;     }
.LBB0_427:
	s_andn2_saveexec_b64 s[76:77], s[76:77]
	v_lshl_or_b32 v0, s84, 8, v24
	s_or_b64 exec, exec, s[76:77]
	s_waitcnt vmcnt(0)
	v_lshlrev_b64 v[14:15], 2, v[0:1]
	v_lshl_add_u64 v[2:3], s[50:51], 0, v[14:15]
	v_add_co_u32_e32 v4, vcc, 0x1000, v2
	s_movk_i32 s3, 0x2000
	s_nop 0
	v_addc_co_u32_e32 v5, vcc, 0, v3, vcc
	v_add_co_u32_e32 v6, vcc, s3, v2
	v_lshl_add_u64 v[10:11], s[52:53], 0, v[14:15]
	s_nop 0
	v_addc_co_u32_e32 v7, vcc, 0, v3, vcc
	s_waitcnt lgkmcnt(0)
	v_add_co_u32_e32 v8, vcc, 0x3000, v2
	s_xor_b64 s[0:1], s[0:1], -1
	s_nop 0
	v_addc_co_u32_e32 v9, vcc, 0, v3, vcc
	global_load_dwordx2 v[2:3], v[2:3], off
	s_nop 0
	global_load_dwordx2 v[4:5], v[4:5], off
	s_nop 0
	global_load_dwordx2 v[6:7], v[6:7], off
	s_nop 0
	global_load_dwordx2 v[8:9], v[8:9], off
	s_add_i32 s2, s2, -1
	global_load_dwordx2 v[10:11], v[10:11], off
	s_mul_hi_i32 s79, s2, 3
	s_mul_i32 s78, s2, 3
	s_add_u32 s2, s40, s44
	s_addc_u32 s3, s41, s45
	v_readlane_b32 s16, v254, 56
	v_ashrrev_i32_e32 v28, 3, v27
	s_mul_i32 s3, s3, 3
	s_mul_hi_u32 s14, s2, 3
	v_readlane_b32 s20, v254, 60
	v_readlane_b32 s21, v254, 61
	v_cndmask_b32_e64 v13, 0, 1, s[0:1]
	v_and_b32_e32 v12, 0xffffffe0, v28
	v_lshl_add_u64 v[22:23], v[0:1], 1, s[46:47]
	s_add_i32 s77, s14, s3
	s_mul_i32 s76, s2, 3
	v_lshl_add_u64 v[20:21], s[20:21], 0, v[14:15]
	v_cmp_gt_i32_e64 s[40:41], 32, v28
	v_cmp_ne_u32_e64 s[0:1], 1, v13
	v_readlane_b32 s17, v254, 57
	v_readlane_b32 s18, v254, 58
	v_readlane_b32 s19, v254, 59
	v_readlane_b32 s22, v254, 62
	v_readlane_b32 s23, v254, 63
	v_readlane_b32 s24, v255, 0
	v_readlane_b32 s25, v255, 1
	v_readlane_b32 s26, v255, 2
	v_readlane_b32 s27, v255, 3
	v_readlane_b32 s28, v255, 4
	v_readlane_b32 s29, v255, 5
	v_readlane_b32 s30, v255, 6
	v_readlane_b32 s31, v255, 7
	s_and_saveexec_b64 s[2:3], s[40:41]
	s_xor_b64 s[80:81], exec, s[2:3]
	s_cbranch_execz .LBB0_435
	s_and_b64 vcc, exec, s[0:1]
	s_mov_b64 s[82:83], -1
	s_cbranch_vccnz .LBB0_432
	v_ashrrev_i32_e32 v13, 31, v12
	v_lshl_add_u64 v[14:15], s[78:79], 0, v[12:13]
	v_lshlrev_b64 v[14:15], 11, v[14:15]
	v_lshl_add_u64 v[14:15], v[22:23], 0, v[14:15]
	global_load_dword v13, v[14:15], off
	global_load_dword v112, v[14:15], off offset:2048
	s_mov_b64 s[100:101], 0x1000
	v_lshl_add_u64 v[114:115], v[14:15], 0, s[100:101]
	global_load_dword v113, v[114:115], off
	s_mov_b64 s[82:83], 0
	s_waitcnt vmcnt(0)
	v_lshlrev_b32_e32 v14, 16, v13
	v_and_b32_e32 v15, 0xffff0000, v13

; __device__ __forceinline__ bfr f2bf(float f) { return (bfr)(pack2(f, f) & 0xffffu); }
; __device__ __forceinline__ float bf2f(bfr b) { return __uint_as_float(((unsigned)b) << 16); }
; __device__ void ssd_pre(const KP& p, int l, int cid, int g) {
;     ...
;     for (int k = 0; k < 3; ++k) {
;       int rr = rs_ - 3 + k;
;       float x0 = 0.f, x1 = 0.f;
;       if (rr >= 0) { unsigned u = *(const unsigned*)(proj + (size_t)(r0 + rr) * NIN + 512 + ch); x0 = __uint_as_float(u << 16); x1 = __uint_as_float(u & 0xffff0000u); }
;       else if (!first) { unsigned u = *(const unsigned*)(tails + ((size_t)(cid - 1) * 3 + (rr + 3)) * 1024 + ch); x0 = __uint_as_float(u << 16); x1 = __uint_as_float(u & 0xffff0000u); }
;       else if (!prompt) { const float* sp = p.in[2] + (((size_t)l * 8 + sb) * 3 + (rr + 3)) * 1024 + ch; x0 = bf2f(f2bf(sp[0])); x1 = bf2f(f2bf(sp[1])); }
;       a0[k] = x0; a1[k] = x1;
.LBB0_435:
	s_andn2_saveexec_b64 s[80:81], s[80:81]
	s_cbranch_execz .LBB0_437
	v_add3_u32 v13, v12, s86, -3
	v_mov_b64_e32 v[14:15], s[36:37]
	s_movk_i32 s2, 0x1c00
	v_mad_i64_i32 v[14:15], s[2:3], v13, s2, v[14:15]
	v_lshl_add_u64 v[14:15], v[0:1], 1, v[14:15]
	global_load_dword v13, v[14:15], off offset:1024
	s_mov_b64 s[98:99], 0x1c00
	v_lshl_add_u64 v[114:115], v[14:15], 0, s[98:99]
	global_load_dword v112, v[114:115], off offset:1024
	v_lshl_add_u64 v[116:117], v[114:115], 0, s[98:99]
	global_load_dword v113, v[116:117], off offset:1024
	s_waitcnt vmcnt(0)
	v_lshlrev_b32_e32 v14, 16, v13
	v_and_b32_e32 v15, 0xffff0000, v13
.LBB0_437:
	s_or_b64 exec, exec, s[80:81]
	s_and_saveexec_b64 s[2:3], s[40:41]
	s_xor_b64 s[80:81], exec, s[2:3]
	s_cbranch_execz .LBB0_443
	s_and_b64 vcc, exec, s[0:1]
	s_mov_b64 s[82:83], -1
	s_cbranch_vccnz .LBB0_440
	v_mov_b32_e32 v13, v112
	s_mov_b64 s[82:83], 0
	v_lshlrev_b32_e32 v16, 16, v13
	v_and_b32_e32 v17, 0xffff0000, v13

; __device__ __forceinline__ bfr f2bf(float f) { return (bfr)(pack2(f, f) & 0xffffu); }
; __device__ __forceinline__ float bf2f(bfr b) { return __uint_as_float(((unsigned)b) << 16); }
; __device__ void ssd_pre(const KP& p, int l, int cid, int g) {
;     ...
;     for (int k = 0; k < 3; ++k) {
;       int rr = rs_ - 3 + k;
;       float x0 = 0.f, x1 = 0.f;
;       if (rr >= 0) { unsigned u = *(const unsigned*)(proj + (size_t)(r0 + rr) * NIN + 512 + ch); x0 = __uint_as_float(u << 16); x1 = __uint_as_float(u & 0xffff0000u); }
;       else if (!first) { unsigned u = *(const unsigned*)(tails + ((size_t)(cid - 1) * 3 + (rr + 3)) * 1024 + ch); x0 = __uint_as_float(u << 16); x1 = __uint_as_float(u & 0xffff0000u); }
;       else if (!prompt) { const float* sp = p.in[2] + (((size_t)l * 8 + sb) * 3 + (rr + 3)) * 1024 + ch; x0 = bf2f(f2bf(sp[0])); x1 = bf2f(f2bf(sp[1])); }
;       a0[k] = x0; a1[k] = x1;
.LBB0_443:
	s_andn2_saveexec_b64 s[80:81], s[80:81]
	s_cbranch_execz .LBB0_445
	v_mov_b32_e32 v13, v112
	v_lshlrev_b32_e32 v16, 16, v13
	v_and_b32_e32 v17, 0xffff0000, v13
.LBB0_445:
	s_or_b64 exec, exec, s[80:81]
	s_and_saveexec_b64 s[2:3], s[40:41]
	s_xor_b64 s[40:41], exec, s[2:3]
	s_cbranch_execz .LBB0_451
	s_and_b64 vcc, exec, s[0:1]
	s_mov_b64 s[0:1], -1
	s_cbranch_vccnz .LBB0_448
	v_mov_b32_e32 v13, v113
	s_mov_b64 s[0:1], 0
	v_lshlrev_b32_e32 v18, 16, v13
	v_and_b32_e32 v19, 0xffff0000, v13

; __device__ __forceinline__ bfr f2bf(float f) { return (bfr)(pack2(f, f) & 0xffffu); }
; __device__ __forceinline__ float bf2f(bfr b) { return __uint_as_float(((unsigned)b) << 16); }
; __device__ void ssd_pre(const KP& p, int l, int cid, int g) {
;     ...
;     for (int k = 0; k < 3; ++k) {
;       int rr = rs_ - 3 + k;
;       float x0 = 0.f, x1 = 0.f;
;       if (rr >= 0) { unsigned u = *(const unsigned*)(proj + (size_t)(r0 + rr) * NIN + 512 + ch); x0 = __uint_as_float(u << 16); x1 = __uint_as_float(u & 0xffff0000u); }
;       else if (!first) { unsigned u = *(const unsigned*)(tails + ((size_t)(cid - 1) * 3 + (rr + 3)) * 1024 + ch); x0 = __uint_as_float(u << 16); x1 = __uint_as_float(u & 0xffff0000u); }
;       else if (!prompt) { const float* sp = p.in[2] + (((size_t)l * 8 + sb) * 3 + (rr + 3)) * 1024 + ch; x0 = bf2f(f2bf(sp[0])); x1 = bf2f(f2bf(sp[1])); }
;       a0[k] = x0; a1[k] = x1;
.LBB0_451:
	s_andn2_saveexec_b64 s[0:1], s[40:41]
	s_cbranch_execz .LBB0_453
	v_mov_b32_e32 v13, v113
	v_lshlrev_b32_e32 v18, 16, v13
	v_and_b32_e32 v19, 0xffff0000, v13
